# next-phase code lines touched with scalar loads at each grid-barrier entry (64KB per barrier, spread over the XCD's waves)
# baseline (speedup 1.0000x reference)
; #define LAS __attribute__((address_space(3)))
; __global__ void __launch_bounds__(NWAVES * 64, 2) mega_fwd(Args args) {
;     extern __shared__ __attribute__((aligned(16))) unsigned char lds[];
;     LAS unsigned char* L = (LAS unsigned char*)lds;
;     volatile LAS unsigned* MISC = (volatile LAS unsigned*)(L + MISC_OFF);
;     const int tid = threadIdx.x, lane = tid & 63, wave = __builtin_amdgcn_readfirstlane(tid >> 6);
;     const int G = gridDim.x; const int bx = blockIdx.x; const int vcu = (G % 8 == 0) ? (bx % 8) * (G / 8) + bx / 8 : bx;
_Z8mega_fwd4Args:
	s_mov_b32 s73, s2
	v_writelane_b32 v244, s73, 63
	v_readfirstlane_b32 s2, v0
	s_load_dword s78, s[0:1], 0xd8
	s_load_dwordx2 s[54:55], s[0:1], 0xd0
	s_load_dwordx4 s[80:83], s[0:1], 0xc0
	v_writelane_b32 v245, s2, 0
	s_add_u32 s2, s0, 0xd8
	s_addc_u32 s3, s1, 0
	v_writelane_b32 v245, s2, 1
	s_mov_b32 s86, s73
	s_nop 0
	v_writelane_b32 v245, s3, 2
	s_waitcnt lgkmcnt(0)
	s_and_b32 s2, s78, 7
	s_cmp_lg_u32 s2, 0
	s_cbranch_scc0 .LBB0_43
	s_movk_i32 s2, 0x80
	v_cmp_gt_u32_e32 vcc, s2, v0
	s_and_saveexec_b64 s[2:3], vcc

; __device__ __forceinline__ void xcd_barrier(const XcdBarrier& b) {
;     asm volatile("s_waitcnt vmcnt(0)" ::: "memory");
;     __syncthreads();
;     if (threadIdx.x == 0) {
;         unsigned* bar = b.bar;
;         __builtin_amdgcn_s_waitcnt(0);
;         unsigned nloc = b.st[0], nx = b.st[1];
;         if (nloc == 0u) { xcd_barrier_complete(bar, b.x, nloc, nx); b.st[0] = nloc; b.st[1] = nx; }
.LBB0_32:
	s_or_b64 exec, exec, s[0:1]
	v_readlane_b32 s100, v244, 63
	v_readfirstlane_b32 s98, v0
	s_lshr_b32 s100, s100, 3
	s_lshr_b32 s98, s98, 6
	s_lshl_b32 s100, s100, 10
	s_and_b32 s98, s98, 7
	s_lshl_b32 s98, s98, 7
	s_add_u32 s100, s100, s98
	s_add_u32 s101, s100, 0x8000
	s_min_u32 s100, s100, (.Lfunc_end0-.Lcodepf0-64)
	s_min_u32 s101, s101, (.Lfunc_end0-.Lcodepf0-64)
	s_getpc_b64 s[98:99]
.Lcodepf0:
	s_load_dword s100, s[98:99], s100
	s_load_dword s101, s[98:99], s101
	s_waitcnt vmcnt(0)
	s_barrier
	s_mov_b64 s[0:1], exec
	v_readlane_b32 s2, v245, 3
	v_readlane_b32 s3, v245, 4
	s_and_b64 s[2:3], s[0:1], s[2:3]
	s_mov_b64 exec, s[2:3]
	s_cbranch_execz .LBB0_85
	s_add_i32 s2, 0, 0x23f60
	v_mov_b32_e32 v1, s2
	s_waitcnt vmcnt(0) expcnt(0) lgkmcnt(0)
	ds_read_b32 v3, v1
	s_add_i32 s2, 0, 0x23f64
	v_mov_b32_e32 v1, s2
	ds_read_b32 v1, v1
	s_waitcnt lgkmcnt(1)
	v_cmp_ne_u32_e32 vcc, 0, v3
	s_cbranch_vccnz .LBB0_49
	v_readlane_b32 s2, v245, 1
	v_readlane_b32 s3, v245, 2
	s_load_dwordx2 s[6:7], s[2:3], 0x4
	s_add_u32 s2, s54, 0x4200
	s_addc_u32 s3, s55, 0
	s_add_u32 s4, s54, 0x4400
	s_addc_u32 s5, s55, 0
	s_waitcnt lgkmcnt(0)
	s_mul_i32 s33, s6, s78
	s_add_u32 s6, s54, 0x4500
	s_mul_i32 s33, s33, s7
	s_addc_u32 s7, s55, 0
	s_add_u32 s12, s54, 0x4600
	s_addc_u32 s13, s55, 0
	s_add_u32 s14, s54, 0x4700
	s_addc_u32 s15, s55, 0
	s_add_u32 s16, s54, 0x4800
	s_addc_u32 s17, s55, 0
	s_add_u32 s18, s54, 0x4900
	s_addc_u32 s19, s55, 0
	s_add_u32 s20, s54, 0x4a00
	s_addc_u32 s21, s55, 0
	s_add_u32 s22, s54, 0x4b00
	s_addc_u32 s23, s55, 0
	s_add_u32 s24, s54, 0x4c00
	s_addc_u32 s25, s55, 0
	s_add_u32 s26, s54, 0x4d00
	s_addc_u32 s27, s55, 0
	s_add_u32 s28, s54, 0x4e00
	s_addc_u32 s29, s55, 0
	s_add_u32 s30, s54, 0x4f00
	s_addc_u32 s31, s55, 0
	s_add_u32 s34, s54, 0x5000
	s_addc_u32 s35, s55, 0
	s_add_u32 s36, s54, 0x5100
	s_addc_u32 s37, s55, 0
	s_add_u32 s38, s54, 0x5200
	s_addc_u32 s39, s55, 0
	s_add_u32 s40, s54, 0x5300
	s_addc_u32 s41, s55, 0
	s_mov_b32 s48, 1
	v_mov_b32_e32 v17, 0
	s_branch .LBB0_36

;   __device__ __forceinline__ bool next(int i,AttnUnit&u)const{ if(i>=2)return false; const int s=vcu&3; u.bh=vcu>>2; u.qb=(i==0)?s:7-s; return true; }
;   __device__ __forceinline__ bool next(int,AttnUnit&u)const{ __syncthreads(); if(threadIdx.x==0)*slot=__hip_atomic_fetch_add(ctr,1u,__ATOMIC_RELAXED,__HIP_MEMORY_SCOPE_AGENT); __syncthreads(); const unsigned v=*slot; if(v>=512u)return false; u.qb=7-(int)(v>>6); u.bh=(int)(v&63u); return true; }
;     __host__ __device__ bool next(int i, Unit& u) const {
;         const long L = (long)i * G + c; if (L >= nwg) return false;
;         int wgid = (int)L; { const int q = nwg / NXCD, r = nwg % NXCD, xcd = wgid % NXCD, off = wgid / NXCD; wgid = (xcd < r ? xcd * (q + 1) : r * (q + 1) + (xcd - r) * q) + off; }
;         const int nig = WGM * nN, gid = wgid / nig, fm = gid * WGM, gsz = (nM - fm) < WGM ? (nM - fm) : WGM;
;         u.pm = fm + ((wgid % nig) % gsz); u.pn = (wgid % nig) / gsz; return true;
; __global__ void __launch_bounds__(NWAVES * 64, 2) mega_fwd(Args args) {
;     ...
;     {   pg8::Gemm g{XB, Wgu1, M, NGU, DM, 0}; pg8::StaticOrder S; S.init(M, NGU, G, bx); pg8::EpiSwiGLU E{H, FF, 0};
;         pg8::gemm_phase<pg8::EpiSwiGLU, pg8::StaticOrder, true, true>(L + RING_OFF, g, S, E);
.LBB0_85:
	s_or_b64 exec, exec, s[0:1]
	s_waitcnt lgkmcnt(0)
	s_add_u32 s58, s54, 0x5200000
	s_addc_u32 s59, s55, 0
	s_cmpk_lt_i32 s73, 0x5ac
	v_mov_b32_e32 v10, v0
	s_cselect_b64 s[0:1], -1, 0
	s_waitcnt lgkmcnt(0)
	s_barrier
	v_writelane_b32 v245, s0, 55
	s_cmpk_gt_i32 s73, 0x5ab
	v_readfirstlane_b32 s2, v10
	v_writelane_b32 v245, s1, 56
	s_cbranch_scc1 .LBB0_109
	s_ashr_i32 s26, s73, 31
	s_lshr_b32 s0, s26, 29
	s_add_i32 s3, s73, s0
	s_and_b32 s0, s3, -8
	s_sub_i32 s5, s73, s0
	s_cmp_gt_i32 s5, 3
	s_cbranch_scc0 .LBB0_88
	s_mul_i32 s0, s5, 0xb5
	s_add_i32 s4, s0, 4
	s_cbranch_execz .LBB0_89
	s_branch .LBB0_90

; __device__ __forceinline__ void xcd_barrier(const XcdBarrier& b) {
;     asm volatile("s_waitcnt vmcnt(0)" ::: "memory");
;     __syncthreads();
;     if (threadIdx.x == 0) {
;         unsigned* bar = b.bar;
;         __builtin_amdgcn_s_waitcnt(0);
;         unsigned nloc = b.st[0], nx = b.st[1];
;         if (nloc == 0u) { xcd_barrier_complete(bar, b.x, nloc, nx); b.st[0] = nloc; b.st[1] = nx; }
.LBB0_116:
	v_readlane_b32 s100, v244, 63
	v_readfirstlane_b32 s98, v0
	s_lshr_b32 s100, s100, 3
	s_lshr_b32 s98, s98, 6
	s_lshl_b32 s100, s100, 10
	s_and_b32 s98, s98, 7
	s_lshl_b32 s98, s98, 7
	s_add_u32 s100, s100, s98
	s_add_u32 s101, s100, 0x8000
	s_min_u32 s100, s100, (.Lfunc_end0-.Lcodepf1-64)
	s_min_u32 s101, s101, (.Lfunc_end0-.Lcodepf1-64)
	s_getpc_b64 s[98:99]
.Lcodepf1:
	s_load_dword s100, s[98:99], s100
	s_load_dword s101, s[98:99], s101
	s_waitcnt vmcnt(0)
	s_waitcnt vmcnt(0)
	s_barrier
	s_mov_b64 s[0:1], exec
	v_readlane_b32 s2, v245, 3
	v_readlane_b32 s3, v245, 4
	s_and_b64 s[2:3], s[0:1], s[2:3]
	s_mov_b64 exec, s[2:3]
	s_cbranch_execz .LBB0_168
	s_add_i32 s2, 0, 0x23f60
	v_mov_b32_e32 v1, s2
	s_waitcnt vmcnt(0) expcnt(0) lgkmcnt(0)
	ds_read_b32 v3, v1
	s_add_i32 s2, 0, 0x23f64
	v_mov_b32_e32 v1, s2
	ds_read_b32 v1, v1
	s_waitcnt lgkmcnt(1)
	v_cmp_ne_u32_e32 vcc, 0, v3
	s_cbranch_vccnz .LBB0_132
	v_readlane_b32 s2, v245, 1
	v_readlane_b32 s3, v245, 2
	s_load_dwordx2 s[6:7], s[2:3], 0x4
	s_add_u32 s2, s54, 0x4200
	s_addc_u32 s3, s55, 0
	s_add_u32 s4, s54, 0x4400
	s_addc_u32 s5, s55, 0
	s_waitcnt lgkmcnt(0)
	s_mul_i32 s49, s6, s78
	s_add_u32 s6, s54, 0x4500
	s_mul_i32 s49, s49, s7
	s_addc_u32 s7, s55, 0
	s_add_u32 s10, s54, 0x4600
	s_addc_u32 s11, s55, 0
	s_add_u32 s12, s54, 0x4700
	s_addc_u32 s13, s55, 0
	s_add_u32 s14, s54, 0x4800
	s_addc_u32 s15, s55, 0
	s_add_u32 s16, s54, 0x4900
	s_addc_u32 s17, s55, 0
	s_add_u32 s20, s54, 0x4a00
	s_addc_u32 s21, s55, 0
	s_add_u32 s22, s54, 0x4b00
	s_addc_u32 s23, s55, 0
	s_add_u32 s24, s54, 0x4c00
	s_addc_u32 s25, s55, 0
	s_add_u32 s26, s54, 0x4d00
	s_addc_u32 s27, s55, 0
	s_add_u32 s28, s54, 0x4e00
	s_addc_u32 s29, s55, 0
	s_add_u32 s30, s54, 0x4f00
	s_addc_u32 s31, s55, 0
	s_add_u32 s34, s54, 0x5000
	s_addc_u32 s35, s55, 0
	s_add_u32 s36, s54, 0x5100
	s_addc_u32 s37, s55, 0
	s_add_u32 s38, s54, 0x5200
	s_addc_u32 s39, s55, 0
	s_add_u32 s40, s54, 0x5300
	s_addc_u32 s41, s55, 0
	s_mov_b32 s52, 1
	v_mov_b32_e32 v17, 0
	s_branch .LBB0_120

; __global__ void __launch_bounds__(NWAVES * 64, 2) mega_fwd(Args args) {
;     ...
;     const unsigned poison0 = (__hip_atomic_load((unsigned*)(ctl + 0), RLX_AGENT) != 0u);
;     {   pg8::Gemm g{H, Wd1, MP, DM, FF, 0}; pg8::StaticOrder S; S.init(MP, DM, G, bx);
;     ...
;         pg8::EpiLnAff E{in[0], nullptr, nullptr, X1B, in[7], in[8], st, DM, 0.5f, ALPHA, poison0};
;         pg8::gemm_phase<pg8::EpiLnAff, pg8::StaticOrder, false, true>(L + RING_OFF, g, S, E);
.LBB0_168:
	s_or_b64 exec, exec, s[0:1]
	s_waitcnt lgkmcnt(0)
	v_mov_b32_e32 v3, 0
	s_waitcnt lgkmcnt(0)
	s_barrier
	global_load_dword v1, v3, s[54:55] sc1
	s_add_u32 s0, s54, 0x13200000
	s_addc_u32 s1, s55, 0
	v_writelane_b32 v245, s0, 57
	s_cmpk_lt_i32 s73, 0x100
	v_mov_b32_e32 v2, v0
	v_writelane_b32 v245, s1, 58
	s_cselect_b64 s[0:1], -1, 0
	v_writelane_b32 v245, s0, 59
	s_cmpk_gt_i32 s73, 0xff
	v_readfirstlane_b32 s24, v2
	v_writelane_b32 v245, s1, 60
	s_waitcnt vmcnt(0)
	v_cmp_ne_u32_e64 s[70:71], 0, v1
	s_cbranch_scc1 .LBB0_236
	s_ashr_i32 s28, s73, 31
	s_lshr_b32 s0, s28, 29
	s_add_i32 s3, s73, s0
	s_and_b32 s0, s3, -8
	s_sub_i32 s4, s73, s0
	s_cmp_gt_i32 s4, -1
	s_cbranch_scc0 .LBB0_171
	s_lshl_b32 s2, s4, 5
	s_cbranch_execz .LBB0_172
	s_branch .LBB0_173

; __device__ __forceinline__ unsigned pk2(float lo, float hi) { f32x2_p v = {lo, hi}; bf16x2_p b = __builtin_convertvector(v, bf16x2_p); return __builtin_bit_cast(unsigned, b); }
; #define SDPP(x, ctrl) __builtin_bit_cast(float, __builtin_amdgcn_update_dpp(0, __builtin_bit_cast(int, (x)), (ctrl), 0xF, 0xF, false))
; __device__ __forceinline__ void xcd_barrier(const XcdBarrier& b) {
;     asm volatile("s_waitcnt vmcnt(0)" ::: "memory");
;     __syncthreads();
;     if (threadIdx.x == 0) {
;         unsigned* bar = b.bar;
;         __builtin_amdgcn_s_waitcnt(0);
;         unsigned nloc = b.st[0], nx = b.st[1];
;         if (nloc == 0u) { xcd_barrier_complete(bar, b.x, nloc, nx); b.st[0] = nloc; b.st[1] = nx; }
; __device__ __forceinline__ void thin_gemm_ln(const bf16* A, const bf16* Bt, int K, const float* base, float s, const float* g, const float* b, float* outf, bf16* outb, ...
;     ...
;     asm volatile("s_waitcnt vmcnt(0) lgkmcnt(0)" ::: "memory"); __syncthreads();
;     const bool bad = flag[0] != 0u;
;     const unsigned long long wv = __hip_atomic_load(slots + (size_t)grow * 16 + cg, __ATOMIC_RELAXED, __HIP_MEMORY_SCOPE_AGENT);
;     const float mj = __uint_as_float((unsigned)wv), m2j = __uint_as_float((unsigned)(wv >> 32));
;     float ms = mj; ms += SDPP(ms, 0xB1); ms += SDPP(ms, 0x4E); ms += SDPP(ms, 0x141); ms += SDPP(ms, 0x140);
;     const float mean = ms * (1.f / 16.f); const float dm = mj - mean;
;     float qq = m2j + 64.f * dm * dm; qq += SDPP(qq, 0xB1); qq += SDPP(qq, 0x4E); qq += SDPP(qq, 0x141); qq += SDPP(qq, 0x140);
;     const float rstd = 1.0f / sqrtf(qq * (1.f / DM) + LN_EPS);
;     f32x4m o = (v - mean) * rstd * *(const f32x4m*)(g + gcol) + *(const f32x4m*)(b + gcol);
;     if (bad) { const float qn = __builtin_nanf(""); o = (f32x4m){qn, qn, qn, qn}; }
;     *(f32x4m*)(outf + (size_t)grow * DM + gcol) = o;
;     if (outb) *(unsigned long long*)(outb + (size_t)grow * DM + gcol) = (unsigned long long)pk2(o.x, o.y) | ((unsigned long long)pk2(o.z, o.w) << 32);
;     __syncthreads();
.LBB0_263:
	s_add_u32 s16, s54, 0x13000000
	s_addc_u32 s17, s55, 0
	s_add_i32 s0, 0, 0x23f88
	v_lshl_add_u64 v[10:11], s[6:7], 0, v[10:11]
	v_lshlrev_b32_e32 v20, 3, v1
	v_mov_b32_e32 v21, 0
	v_mov_b32_e32 v3, s0
	v_lshl_add_u64 v[10:11], v[10:11], 0, v[20:21]
	s_waitcnt vmcnt(0) lgkmcnt(0)
	s_waitcnt lgkmcnt(0)
	s_barrier
	ds_read_b32 v26, v3
	global_load_dwordx2 v[22:23], v[10:11], off sc1
	v_readlane_b32 s0, v245, 5
	v_readlane_b32 s1, v245, 6
	v_readlane_b32 s2, v245, 7
	v_readlane_b32 s3, v245, 8
	v_readlane_b32 s4, v245, 9
	v_readlane_b32 s5, v245, 10
	v_readlane_b32 s6, v245, 11
	v_readlane_b32 s7, v245, 12
	v_readlane_b32 s8, v245, 13
	v_readlane_b32 s9, v245, 14
	v_readlane_b32 s10, v245, 15
	v_readlane_b32 s11, v245, 16
	v_readlane_b32 s12, v245, 17
	v_readlane_b32 s13, v245, 18
	v_readlane_b32 s14, v245, 19
	v_readlane_b32 s15, v245, 20
	v_lshl_add_u64 v[24:25], v[8:9], 1, s[54:55]
	v_mov_b32_e32 v3, v21
	v_lshlrev_b32_e32 v20, 1, v14
	v_lshl_add_u64 v[14:15], v[24:25], 0, v[20:21]
	v_mov_b32_e32 v1, 0x3727c5ac
	global_load_dwordx4 v[10:13], v2, s[14:15]
	v_readlane_b32 s0, v245, 21
	v_readlane_b32 s1, v245, 22
	v_readlane_b32 s2, v245, 23
	v_readlane_b32 s3, v245, 24
	v_readlane_b32 s4, v245, 25
	v_readlane_b32 s5, v245, 26
	v_readlane_b32 s6, v245, 27
	global_load_dwordx4 v[16:19], v2, s[0:1]
	v_readlane_b32 s7, v245, 28
	v_readlane_b32 s8, v245, 29
	v_readlane_b32 s9, v245, 30
	v_readlane_b32 s10, v245, 31
	v_readlane_b32 s11, v245, 32
	v_readlane_b32 s12, v245, 33
	v_readlane_b32 s13, v245, 34
	v_readlane_b32 s14, v245, 35
	v_readlane_b32 s15, v245, 36
	v_writelane_b32 v245, s16, 61
	s_mov_b32 s0, 0xf800000
	v_mov_b32_e32 v27, 0x260
	v_lshl_add_u64 v[8:9], v[8:9], 2, s[16:17]
	v_lshl_add_u64 v[8:9], v[8:9], 0, v[2:3]
	s_mov_b32 s2, 0x15200000
	v_mov_b32_e32 v28, 0x7fc00000
	v_writelane_b32 v245, s17, 62
	s_waitcnt vmcnt(2)
	v_add_f32_dpp v2, v22, v22 quad_perm:[1,0,3,2] row_mask:0xf bank_mask:0xf bound_ctrl:1
	s_nop 1
	v_add_f32_dpp v2, v2, v2 quad_perm:[2,3,0,1] row_mask:0xf bank_mask:0xf bound_ctrl:1
	s_nop 1
	v_add_f32_dpp v2, v2, v2 row_half_mirror row_mask:0xf bank_mask:0xf bound_ctrl:1
	s_nop 1
	v_add_f32_dpp v2, v2, v2 row_mirror row_mask:0xf bank_mask:0xf bound_ctrl:1
	v_fmamk_f32 v3, v2, 0xbd800000, v22
	v_mul_f32_e32 v20, 0x42800000, v3
	v_fmac_f32_e32 v23, v3, v20
	v_fmamk_f32 v5, v2, 0xbd800000, v5
	v_fmac_f32_e32 v4, 0xbd800000, v2
	v_add_f32_dpp v3, v23, v23 quad_perm:[1,0,3,2] row_mask:0xf bank_mask:0xf bound_ctrl:1
	v_fmamk_f32 v7, v2, 0xbd800000, v7
	v_fmac_f32_e32 v6, 0xbd800000, v2
	v_add_f32_dpp v3, v3, v3 quad_perm:[2,3,0,1] row_mask:0xf bank_mask:0xf bound_ctrl:1
	s_nop 1
	v_add_f32_dpp v3, v3, v3 row_half_mirror row_mask:0xf bank_mask:0xf bound_ctrl:1
	s_nop 1
	v_add_f32_dpp v3, v3, v3 row_mirror row_mask:0xf bank_mask:0xf bound_ctrl:1
	v_fmac_f32_e32 v1, 0x3a800000, v3
	v_mul_f32_e32 v3, 0x4f800000, v1
	v_cmp_gt_f32_e32 vcc, s0, v1
	s_nop 1
	v_cndmask_b32_e32 v1, v1, v3, vcc
	v_sqrt_f32_e32 v3, v1
	s_nop 0
	v_add_u32_e32 v20, -1, v3
	v_add_u32_e32 v21, 1, v3
	v_fma_f32 v22, -v20, v3, v1
	v_fma_f32 v23, -v21, v3, v1
	v_cmp_ge_f32_e64 s[0:1], 0, v22
	s_nop 1
	v_cndmask_b32_e64 v3, v3, v20, s[0:1]
	v_cmp_lt_f32_e64 s[0:1], 0, v23
	s_nop 1
	v_cndmask_b32_e64 v3, v3, v21, s[0:1]
	v_mul_f32_e32 v20, 0x37800000, v3
	v_cndmask_b32_e32 v3, v3, v20, vcc
	v_cmp_class_f32_e32 vcc, v1, v27
	s_nop 1
	v_cndmask_b32_e32 v1, v3, v1, vcc
	v_div_scale_f32 v3, s[0:1], v1, v1, 1.0
	v_rcp_f32_e32 v20, v3
	v_div_scale_f32 v2, vcc, 1.0, v1, 1.0
	v_fma_f32 v21, -v3, v20, 1.0
	v_fmac_f32_e32 v20, v21, v20
	v_mul_f32_e32 v21, v2, v20
	v_fma_f32 v22, -v3, v21, v2
	v_fmac_f32_e32 v21, v22, v20
	v_fma_f32 v2, -v3, v21, v2
	v_div_fmas_f32 v2, v2, v20, v21
	v_add_co_u32_e32 v14, vcc, s2, v14
	v_div_fixup_f32 v2, v2, v1, 1.0
	s_nop 0
	v_addc_co_u32_e32 v15, vcc, 0, v15, vcc
	v_pk_mul_f32 v[6:7], v[6:7], v[2:3] op_sel_hi:[1,0]
	v_pk_mul_f32 v[2:3], v[4:5], v[2:3] op_sel_hi:[1,0]
	s_waitcnt vmcnt(0)
	v_pk_fma_f32 v[4:5], v[12:13], v[6:7], v[18:19]
	v_pk_fma_f32 v[2:3], v[10:11], v[2:3], v[16:17]
	s_waitcnt lgkmcnt(0)
	v_cmp_eq_u32_e32 vcc, 0, v26
	s_nop 1
	v_cndmask_b32_e32 v5, v28, v5, vcc
	v_cndmask_b32_e32 v4, v28, v4, vcc
	v_cndmask_b32_e32 v3, v28, v3, vcc
	v_cndmask_b32_e32 v2, v28, v2, vcc
	global_store_dwordx4 v[8:9], v[2:5], off
	s_nop 1
	v_cvt_pk_bf16_f32 v2, v2, v3
	v_cvt_pk_bf16_f32 v3, v4, v5
	global_store_dwordx2 v[14:15], v[2:3], off
	s_barrier
	v_readlane_b32 s100, v244, 63
	v_readfirstlane_b32 s98, v0
	s_lshr_b32 s100, s100, 3
	s_lshr_b32 s98, s98, 6
	s_lshl_b32 s100, s100, 10
	s_and_b32 s98, s98, 7
	s_lshl_b32 s98, s98, 7
	s_add_u32 s100, s100, s98
	s_add_u32 s101, s100, 0x8000
	s_min_u32 s100, s100, (.Lfunc_end0-.Lcodepf2-64)
	s_min_u32 s101, s101, (.Lfunc_end0-.Lcodepf2-64)
	s_getpc_b64 s[98:99]
.Lcodepf2:
	s_load_dword s100, s[98:99], s100
	s_load_dword s101, s[98:99], s101
	s_waitcnt vmcnt(0)
	s_barrier
	s_mov_b64 s[0:1], exec
	v_readlane_b32 s2, v245, 3
	v_readlane_b32 s3, v245, 4
	s_and_b64 s[2:3], s[0:1], s[2:3]
	s_mov_b64 exec, s[2:3]
	s_cbranch_execz .LBB0_315
	s_add_i32 s2, 0, 0x23f60
	v_mov_b32_e32 v1, s2
	s_waitcnt vmcnt(0) expcnt(0) lgkmcnt(0)
	ds_read_b32 v3, v1
	s_add_i32 s2, 0, 0x23f64
	v_mov_b32_e32 v1, s2
	ds_read_b32 v1, v1
	s_waitcnt lgkmcnt(1)
	v_cmp_ne_u32_e32 vcc, 0, v3
	s_cbranch_vccnz .LBB0_279
	v_readlane_b32 s2, v245, 1
	v_readlane_b32 s3, v245, 2
	s_load_dwordx2 s[6:7], s[2:3], 0x4
	s_add_u32 s2, s54, 0x4200
	s_addc_u32 s3, s55, 0
	s_add_u32 s4, s54, 0x4400
	s_addc_u32 s5, s55, 0
	s_waitcnt lgkmcnt(0)
	s_mul_i32 s46, s6, s78
	s_add_u32 s6, s54, 0x4500
	s_mul_i32 s46, s46, s7
	s_addc_u32 s7, s55, 0
	s_add_u32 s8, s54, 0x4600
	s_addc_u32 s9, s55, 0
	s_add_u32 s10, s54, 0x4700
	s_addc_u32 s11, s55, 0
	s_add_u32 s12, s54, 0x4800
	s_addc_u32 s13, s55, 0
	s_add_u32 s14, s54, 0x4900
	s_addc_u32 s15, s55, 0
	s_add_u32 s16, s54, 0x4a00
	s_addc_u32 s17, s55, 0
	s_add_u32 s20, s54, 0x4b00
	s_addc_u32 s21, s55, 0
	s_add_u32 s22, s54, 0x4c00
	s_addc_u32 s23, s55, 0
	s_add_u32 s24, s54, 0x4d00
	s_addc_u32 s25, s55, 0
	s_add_u32 s26, s54, 0x4e00
	s_addc_u32 s27, s55, 0
	s_add_u32 s28, s54, 0x4f00
	s_addc_u32 s29, s55, 0
	s_add_u32 s30, s54, 0x5000
	s_addc_u32 s31, s55, 0
	s_add_u32 s34, s54, 0x5100
	s_addc_u32 s35, s55, 0
	s_add_u32 s36, s54, 0x5200
	s_addc_u32 s37, s55, 0
	s_add_u32 s38, s54, 0x5300
	s_addc_u32 s39, s55, 0
	s_mov_b32 s47, 1
	v_mov_b32_e32 v17, 0
	s_branch .LBB0_267

;   __device__ __forceinline__ bool next(int i,AttnUnit&u)const{ if(i>=2)return false; const int s=vcu&3; u.bh=vcu>>2; u.qb=(i==0)?s:7-s; return true; }
;   __device__ __forceinline__ bool next(int,AttnUnit&u)const{ __syncthreads(); if(threadIdx.x==0)*slot=__hip_atomic_fetch_add(ctr,1u,__ATOMIC_RELAXED,__HIP_MEMORY_SCOPE_AGENT); __syncthreads(); const unsigned v=*slot; if(v>=512u)return false; u.qb=7-(int)(v>>6); u.bh=(int)(v&63u); return true; }
;     __host__ __device__ bool next(int i, Unit& u) const {
;         const long L = (long)i * G + c; if (L >= nwg) return false;
;         int wgid = (int)L; { const int q = nwg / NXCD, r = nwg % NXCD, xcd = wgid % NXCD, off = wgid / NXCD; wgid = (xcd < r ? xcd * (q + 1) : r * (q + 1) + (xcd - r) * q) + off; }
;         const int nig = WGM * nN, gid = wgid / nig, fm = gid * WGM, gsz = (nM - fm) < WGM ? (nM - fm) : WGM;
;         u.pm = fm + ((wgid % nig) % gsz); u.pn = (wgid % nig) / gsz; return true;
; __global__ void __launch_bounds__(NWAVES * 64, 2) mega_fwd(Args args) {
;     ...
;     {   pg8::Gemm g{X1B, Win, M, NINP, DM, 0}; pg8::StaticOrder S; S.init(M, NINP, G, bx);
;         pg8::EpiMix E{P, (bf16*)(ws + WS_PB), out, Qb, Kb, Vb, MP, SEQ, DS, attn_body::C2, O_KP, O_VP, O_SCP, O_KS, O_VS, O_SCS};
;         pg8::gemm_phase<pg8::EpiMix, pg8::StaticOrder, true, true>(L + RING_OFF, g, S, E);
.LBB0_315:
	s_or_b64 exec, exec, s[0:1]
	s_waitcnt lgkmcnt(0)
	v_mov_b32_e32 v10, v0
	s_cmpk_lt_i32 s73, 0x3de
	s_waitcnt lgkmcnt(0)
	s_barrier
	s_cselect_b64 s[0:1], -1, 0
	s_cmpk_gt_i32 s73, 0x3dd
	v_readfirstlane_b32 s4, v10
	s_cbranch_scc1 .LBB0_321
	s_ashr_i32 s2, s73, 31
	s_lshr_b32 s2, s2, 29
	s_add_i32 s5, s73, s2
	s_and_b32 s2, s5, -8
	s_sub_i32 s6, s73, s2
	s_cmp_gt_i32 s6, 5
	s_cbranch_scc0 .LBB0_318
	s_mul_i32 s2, s6, 0x7b
	s_add_i32 s7, s2, 6
	s_cbranch_execz .LBB0_319
	s_branch .LBB0_320

; __device__ __forceinline__ void xcd_barrier(const XcdBarrier& b) {
;     asm volatile("s_waitcnt vmcnt(0)" ::: "memory");
;     __syncthreads();
;     if (threadIdx.x == 0) {
;         unsigned* bar = b.bar;
;         __builtin_amdgcn_s_waitcnt(0);
;         unsigned nloc = b.st[0], nx = b.st[1];
;         if (nloc == 0u) { xcd_barrier_complete(bar, b.x, nloc, nx); b.st[0] = nloc; b.st[1] = nx; }
.Lcodepf3:
	s_load_dword s100, s[98:99], s100
	s_load_dword s101, s[98:99], s101
	s_waitcnt vmcnt(0)
	s_waitcnt vmcnt(0)
	s_barrier
	s_mov_b64 s[0:1], exec
	v_readlane_b32 s2, v245, 3
	v_readlane_b32 s3, v245, 4
	s_and_b64 s[2:3], s[0:1], s[2:3]
	s_mov_b64 exec, s[2:3]
	s_cbranch_execz .LBB0_1005
	s_add_i32 s2, 0, 0x23f60
	v_mov_b32_e32 v1, s2
	s_waitcnt vmcnt(0) expcnt(0) lgkmcnt(0)
	ds_read_b32 v3, v1
	s_add_i32 s2, 0, 0x23f64
	v_mov_b32_e32 v1, s2
	ds_read_b32 v1, v1
	s_waitcnt lgkmcnt(1)
	v_cmp_ne_u32_e32 vcc, 0, v3
	s_cbranch_vccnz .LBB0_969
	v_readlane_b32 s2, v245, 1
	v_readlane_b32 s3, v245, 2
	s_load_dwordx2 s[6:7], s[2:3], 0x4
	v_readlane_b32 s36, v244, 24
	v_readlane_b32 s37, v244, 25
	s_add_u32 s2, s36, 0x4200
	s_addc_u32 s3, s37, 0
	s_add_u32 s4, s36, 0x4400
	s_addc_u32 s5, s37, 0
	s_waitcnt lgkmcnt(0)
	s_mul_i32 s33, s6, s67
	s_add_u32 s6, s36, 0x4500
	s_mul_i32 s33, s33, s7
	s_addc_u32 s7, s37, 0
	s_add_u32 s8, s36, 0x4600
	s_addc_u32 s9, s37, 0
	s_add_u32 s10, s36, 0x4700
	s_addc_u32 s11, s37, 0
	s_add_u32 s12, s36, 0x4800
	s_addc_u32 s13, s37, 0
	s_add_u32 s14, s36, 0x4900
	s_addc_u32 s15, s37, 0
	s_add_u32 s16, s36, 0x4a00
	s_addc_u32 s17, s37, 0
	s_add_u32 s18, s36, 0x4b00
	s_addc_u32 s19, s37, 0
	s_add_u32 s20, s36, 0x4c00
	s_addc_u32 s21, s37, 0
	s_add_u32 s22, s36, 0x4d00
	s_addc_u32 s23, s37, 0
	s_add_u32 s24, s36, 0x4e00
	s_addc_u32 s25, s37, 0
	s_add_u32 s26, s36, 0x4f00
	s_addc_u32 s27, s37, 0
	s_add_u32 s28, s36, 0x5000
	s_addc_u32 s29, s37, 0
	s_add_u32 s30, s36, 0x5100
	s_addc_u32 s31, s37, 0
	s_add_u32 s34, s36, 0x5200
	s_addc_u32 s35, s37, 0
	s_add_u32 s36, s36, 0x5300
	s_addc_u32 s37, s37, 0
	s_mov_b32 s44, 1
	v_mov_b32_e32 v17, 0
	s_branch .LBB0_957

; __device__ __forceinline__ void p_gdn_prep(const float* P, const float* sconv, const float* convw, const float* alog, const float* dtb, float* GQ, float* GK, float* GV, float* GG, float* GB, int m0, int vcu, int G, int h, int lane) {
;     for (int m = m0 + vcu; m < M; m += G) {
;         const bool samp = m >= MP; int b, t;
;         if (!samp) { b = m / SEQ; t = m % SEQ; } else { b = (m - MP) / DS; t = (m - MP) % DS; }
;         float r[3];
; #pragma unroll
;         for (int part = 0; part < 3; ++part) {
;             const int c = part * 512 + h * 64 + lane; float acc = 0.f;
; #pragma unroll
;             for (int j = 0; j < 4; ++j) { const int tt = t - 3 + j;
;                 const float* src = (tt >= 0) ? P + (size_t)(m - t + tt) * NINP + C_GQKV + c : sconv + ((size_t)b * 3 + (tt + 3)) * 1536 + c;
;                 acc += *src * convw[j * 1536 + c]; }
;             r[part] = acc / (1.0f + __expf(-acc)); }
;         const float qn = wave_sum(r[0] * r[0]), kn = wave_sum(r[1] * r[1]);
;         GQ[(size_t)m * GW + h * 64 + lane] = r[0] * (1.0f / sqrtf(qn + RMS_EPS)) * 0.125f;
;         GK[(size_t)m * GW + h * 64 + lane] = r[1] * (1.0f / sqrtf(kn + RMS_EPS));
;         GV[(size_t)m * GW + h * 64 + lane] = r[2];
;         if (lane == 0) { const float bb = P[(size_t)m * NINP + C_B + h], aa = P[(size_t)m * NINP + C_A + h] + dtb[h];
.LBB0_1005:
	s_or_b64 exec, exec, s[0:1]
	s_waitcnt lgkmcnt(0)
	v_readlane_b32 s0, v244, 24
	v_readlane_b32 s1, v244, 25
	s_add_u32 s2, s0, 0x26e00000
	s_addc_u32 s3, s1, 0
	v_writelane_b32 v244, s2, 31
	s_waitcnt lgkmcnt(0)
	v_mbcnt_lo_u32_b32 v1, -1, 0
	v_writelane_b32 v244, s3, 32
	s_add_u32 s2, s0, 0x28f00000
	s_addc_u32 s3, s1, 0
	s_add_u32 s68, s0, 0x2b000000
	v_writelane_b32 v244, s2, 33
	s_addc_u32 s69, s1, 0
	s_barrier
	v_writelane_b32 v244, s3, 34
	s_add_u32 s2, s0, 0x2d100000
	v_writelane_b32 v244, s2, 35
	s_addc_u32 s2, s1, 0
	v_writelane_b32 v244, s2, 36
	s_add_u32 s0, s0, 0x2d200000
	v_writelane_b32 v244, s0, 37
	s_addc_u32 s0, s1, 0
	v_writelane_b32 v244, s0, 38
	s_nop 0
	v_readlane_b32 s0, v244, 0
	s_cmpk_gt_i32 s0, 0x1ff
	v_readlane_b32 s1, v244, 1
	s_cbranch_scc1 .LBB0_1064
	v_mbcnt_hi_u32_b32 v3, -1, v1
	v_and_b32_e32 v4, 64, v3
	v_add_u32_e32 v4, 64, v4
	v_xor_b32_e32 v5, 1, v3
	v_cmp_lt_i32_e32 vcc, v5, v4
	v_readlane_b32 s0, v244, 0
	s_add_i32 s12, s0, 0x4000
	v_cndmask_b32_e32 v5, v3, v5, vcc
	v_lshlrev_b32_e32 v42, 2, v5
	v_xor_b32_e32 v5, 2, v3
	v_cmp_lt_i32_e32 vcc, v5, v4
	v_readlane_b32 s0, v245, 0
	s_andn2_b32 s0, s0, 63
	v_cndmask_b32_e32 v5, v3, v5, vcc
	v_lshlrev_b32_e32 v43, 2, v5
	v_xor_b32_e32 v5, 4, v3
	v_cmp_lt_i32_e32 vcc, v5, v4
	v_or_b32_e32 v2, s0, v196
	s_ashr_i32 s0, s0, 31
	v_cndmask_b32_e32 v5, v3, v5, vcc
	v_lshlrev_b32_e32 v44, 2, v5
	v_xor_b32_e32 v5, 8, v3
	v_cmp_lt_i32_e32 vcc, v5, v4
	v_readlane_b32 s16, v245, 39
	v_readlane_b32 s17, v245, 40
	v_cndmask_b32_e32 v5, v3, v5, vcc
	v_lshlrev_b32_e32 v45, 2, v5
	v_xor_b32_e32 v5, 16, v3
	v_cmp_lt_i32_e32 vcc, v5, v4
	v_readlane_b32 s18, v245, 41
	v_readlane_b32 s19, v245, 42
	v_cndmask_b32_e32 v5, v3, v5, vcc
	v_lshlrev_b32_e32 v46, 2, v5
	v_xor_b32_e32 v5, 32, v3
	v_cmp_lt_i32_e32 vcc, v5, v4
	v_readlane_b32 s20, v245, 43
	v_readlane_b32 s21, v245, 44
	v_cndmask_b32_e32 v3, v3, v5, vcc
	v_lshlrev_b32_e32 v47, 2, v3
	v_mov_b32_e32 v3, s0
	s_lshl_b32 s0, s50, 2
	v_readlane_b32 s22, v245, 45
	v_readlane_b32 s23, v245, 46
	v_readlane_b32 s24, v245, 47
	v_readlane_b32 s25, v245, 48
	v_readlane_b32 s26, v245, 49
	v_readlane_b32 s27, v245, 50
	v_readlane_b32 s28, v245, 51
	v_readlane_b32 s29, v245, 52
	v_readlane_b32 s30, v245, 53
	v_readlane_b32 s31, v245, 54
	s_add_u32 s14, s16, s0
	s_addc_u32 s15, s17, 0
	v_readlane_b32 s16, v245, 21
	v_readlane_b32 s30, v245, 35
	v_readlane_b32 s31, v245, 36
	v_readlane_b32 s17, v245, 22
	v_readlane_b32 s18, v245, 23
	v_readlane_b32 s19, v245, 24
	v_readlane_b32 s20, v245, 25
	v_readlane_b32 s21, v245, 26
	v_readlane_b32 s22, v245, 27
	v_readlane_b32 s23, v245, 28
	v_readlane_b32 s24, v245, 29
	v_readlane_b32 s25, v245, 30
	v_readlane_b32 s26, v245, 31
	v_readlane_b32 s27, v245, 32
	v_readlane_b32 s28, v245, 33
	v_readlane_b32 s29, v245, 34
	s_mov_b64 s[58:59], s[30:31]
	s_mov_b64 s[56:57], s[28:29]
	v_ashrrev_i32_e32 v5, 31, v2
	v_mov_b32_e32 v4, v2
	v_readlane_b32 s16, v245, 5
	v_readlane_b32 s1, v244, 1
	v_lshlrev_b64 v[8:9], 2, v[4:5]
	v_readlane_b32 s26, v245, 15
	v_readlane_b32 s27, v245, 16
	v_add_u32_e32 v26, 0x400, v2
	s_add_u32 s34, s58, s0
	v_readlane_b32 s20, v245, 9
	v_readlane_b32 s21, v245, 10
	v_lshl_add_u64 v[6:7], s[26:27], 0, v[8:9]
	v_lshl_add_u64 v[8:9], s[56:57], 0, v[8:9]
	s_mov_b64 s[0:1], 0x3000
	v_add_u32_e32 v16, 0x200, v2
	v_add_u32_e32 v20, 0x800, v2
	v_add_u32_e32 v22, 0xe00, v2
	v_add_u32_e32 v24, 0x1400, v2
	v_ashrrev_i32_e32 v27, 31, v26
	v_add_u32_e32 v32, 0xa00, v2
	v_add_u32_e32 v34, 0x1000, v2
	v_add_u32_e32 v36, 0x1600, v2
	v_readlane_b32 s22, v245, 11
	s_mov_b64 s[20:21], 0x1800
	v_lshl_add_u64 v[12:13], v[8:9], 0, s[0:1]
	s_mov_b64 s[0:1], 0x4800
	v_ashrrev_i32_e32 v17, 31, v16
	v_ashrrev_i32_e32 v21, 31, v20
	v_ashrrev_i32_e32 v23, 31, v22
	v_ashrrev_i32_e32 v25, 31, v24
	v_lshlrev_b64 v[30:31], 2, v[26:27]
	v_ashrrev_i32_e32 v33, 31, v32
	v_ashrrev_i32_e32 v35, 31, v34
	v_ashrrev_i32_e32 v37, 31, v36
	v_cmp_eq_u32_e64 s[4:5], 0, v196
	s_addc_u32 s35, s59, 0
	v_lshl_add_u64 v[10:11], v[8:9], 0, s[20:21]
	v_lshl_add_u64 v[14:15], v[8:9], 0, s[0:1]
	v_lshl_add_u64 v[18:19], v[16:17], 2, s[26:27]
	v_lshl_add_u64 v[20:21], v[20:21], 2, s[56:57]
	v_lshl_add_u64 v[22:23], v[22:23], 2, s[56:57]
	v_lshl_add_u64 v[24:25], v[24:25], 2, s[56:57]
	v_lshl_add_u64 v[28:29], s[26:27], 0, v[30:31]
	v_lshl_add_u64 v[30:31], s[56:57], 0, v[30:31]
	v_lshl_add_u64 v[32:33], v[32:33], 2, s[56:57]
	v_lshl_add_u64 v[34:35], v[34:35], 2, s[56:57]
	v_lshl_add_u64 v[36:37], v[36:37], 2, s[56:57]
	v_mov_b32_e32 v48, 0
	s_mov_b32 s22, 0xf800000
	v_mov_b32_e32 v49, 0x260
	v_mov_b32_e32 v50, 0x3000
	v_mov_b32_e32 v51, 0x3ecc95a3
	v_mov_b32_e32 v52, 0x1800
	v_mov_b32_e32 v38, 0x3f317218
	v_mov_b32_e32 v53, 0x7f800000
	v_mov_b32_e32 v54, 0x7fc00000
	v_mov_b32_e32 v55, 0xff800000
	v_readlane_b32 s17, v245, 6
	v_readlane_b32 s18, v245, 7
	v_readlane_b32 s19, v245, 8
	v_readlane_b32 s23, v245, 12
	v_readlane_b32 s24, v245, 13
	v_readlane_b32 s25, v245, 14
	v_readlane_b32 s28, v245, 17
	v_readlane_b32 s29, v245, 18
	v_readlane_b32 s30, v245, 19
	v_readlane_b32 s31, v245, 20
	s_branch .LBB0_1009

; __device__ __forceinline__ void xcd_barrier(const XcdBarrier& b) {
;     asm volatile("s_waitcnt vmcnt(0)" ::: "memory");
;     __syncthreads();
;     if (threadIdx.x == 0) {
;         unsigned* bar = b.bar;
;         __builtin_amdgcn_s_waitcnt(0);
;         unsigned nloc = b.st[0], nx = b.st[1];
;         if (nloc == 0u) { xcd_barrier_complete(bar, b.x, nloc, nx); b.st[0] = nloc; b.st[1] = nx; }
.Lcodepf4:
	s_load_dword s100, s[98:99], s100
	s_load_dword s101, s[98:99], s101
	s_waitcnt vmcnt(0)
	s_waitcnt lgkmcnt(0)
	s_barrier
	s_mov_b64 s[0:1], exec
	v_readlane_b32 s2, v245, 3
	v_readlane_b32 s3, v245, 4
	s_and_b64 s[2:3], s[0:1], s[2:3]
	s_mov_b64 exec, s[2:3]
	s_cbranch_execz .LBB0_1129
	s_add_i32 s2, 0, 0x23f60
	v_mov_b32_e32 v2, s2
	s_waitcnt vmcnt(0) expcnt(0) lgkmcnt(0)
	ds_read_b32 v4, v2
	s_add_i32 s2, 0, 0x23f64
	v_mov_b32_e32 v2, s2
	ds_read_b32 v2, v2
	s_waitcnt lgkmcnt(1)
	v_cmp_ne_u32_e32 vcc, 0, v4
	s_cbranch_vccnz .LBB0_1093
	v_readlane_b32 s2, v245, 1
	v_readlane_b32 s3, v245, 2
	s_load_dwordx2 s[6:7], s[2:3], 0x4
	v_readlane_b32 s36, v244, 24
	v_readlane_b32 s37, v244, 25
	s_add_u32 s2, s36, 0x4200
	s_addc_u32 s3, s37, 0
	s_add_u32 s4, s36, 0x4400
	s_addc_u32 s5, s37, 0
	s_waitcnt lgkmcnt(0)
	s_mul_i32 s33, s6, s67
	s_add_u32 s6, s36, 0x4500
	s_mul_i32 s33, s33, s7
	s_addc_u32 s7, s37, 0
	s_add_u32 s8, s36, 0x4600
	s_addc_u32 s9, s37, 0
	s_add_u32 s10, s36, 0x4700
	s_addc_u32 s11, s37, 0
	s_add_u32 s12, s36, 0x4800
	s_addc_u32 s13, s37, 0
	s_add_u32 s14, s36, 0x4900
	s_addc_u32 s15, s37, 0
	s_add_u32 s16, s36, 0x4a00
	s_addc_u32 s17, s37, 0
	s_add_u32 s18, s36, 0x4b00
	s_addc_u32 s19, s37, 0
	s_add_u32 s20, s36, 0x4c00
	s_addc_u32 s21, s37, 0
	s_add_u32 s22, s36, 0x4d00
	s_addc_u32 s23, s37, 0
	s_add_u32 s24, s36, 0x4e00
	s_addc_u32 s25, s37, 0
	s_add_u32 s26, s36, 0x4f00
	s_addc_u32 s27, s37, 0
	s_add_u32 s28, s36, 0x5000
	s_addc_u32 s29, s37, 0
	s_add_u32 s30, s36, 0x5100
	s_addc_u32 s31, s37, 0
	s_add_u32 s34, s36, 0x5200
	s_addc_u32 s35, s37, 0
	s_add_u32 s36, s36, 0x5300
	s_addc_u32 s37, s37, 0
	s_mov_b32 s46, 1
	v_mov_b32_e32 v18, 0
	s_branch .LBB0_1081

.LBB0_1129:
	s_or_b64 exec, exec, s[0:1]
	s_waitcnt lgkmcnt(0)
	v_readlane_b32 s0, v244, 24
	v_readlane_b32 s1, v244, 25
	s_add_u32 s42, s0, 0x24c00000
	s_addc_u32 s43, s1, 0
	v_readlane_b32 s0, v244, 0
	s_cmp_lt_i32 s0, 64
	s_waitcnt lgkmcnt(0)
	s_barrier
	v_readlane_b32 s1, v244, 1
	s_mov_b32 s101, 0x20400
	v_and_b32_e32 v246, 0x3ff, v0
	v_cmp_lt_u32_e32 vcc, 0x80, v246
	s_nop 1
	v_cndmask_b32_e64 v247, 0, 1, vcc
	v_cmp_lt_u32_e32 vcc, 0x101, v246
	s_nop 1
	v_cndmask_b32_e64 v248, 0, 1, vcc
	v_add_u32_e32 v247, v247, v248
	v_mul_u32_u24_e32 v249, 0x81, v247
	v_sub_u32_e32 v249, v246, v249
	v_lshlrev_b32_e32 v250, 1, v247
	v_lshlrev_b32_e32 v249, v250, v249
	v_min_u32_e32 v251, 1, v247
	v_add_u32_e32 v251, v249, v251
	v_max_u32_e32 v251, 32, v251
	v_min_u32_e32 v251, 0x81, v251
	v_subrev_u32_e32 v251, 32, v251
	v_add_u32_e32 v252, v249, v248
	v_add_u32_e32 v252, 3, v252
	v_lshrrev_b32_e32 v252, 2, v252
	v_min_u32_e32 v252, 0x81, v252
	v_add_u32_e32 v253, 15, v249
	v_lshrrev_b32_e32 v253, 4, v253
	v_min_u32_e32 v253, 0x81, v253
	v_add3_u32 v251, v251, v252, v253
	v_add_u32_e32 v251, 32, v251
	v_cmp_gt_u32_e32 vcc, 32, v246
	s_nop 1
	v_cndmask_b32_e32 v251, v251, v246, vcc
	v_cmp_lt_u32_e32 vcc, 0x182, v246
	s_nop 1
	v_cndmask_b32_e32 v251, v251, v246, vcc
	v_cmp_gt_u32_e32 vcc, 0x188, v246
	s_and_saveexec_b64 s[98:99], vcc
	v_lshl_add_u32 v252, v251, 2, s101
	ds_write_b32 v252, v246
	s_or_b64 exec, exec, s[98:99]
	s_waitcnt lgkmcnt(0)
	s_barrier
	s_cmp_lt_i32 s0, 64
	s_cbranch_scc0 .LBB0_1220
	v_mov_b32_e32 v114, v0
	v_readlane_b32 s0, v245, 39
	v_lshlrev_b32_e32 v2, 2, v114
	v_and_b32_e32 v112, 60, v2
	v_lshlrev_b32_e32 v86, 2, v112
	v_readlane_b32 s2, v245, 41
	v_readlane_b32 s3, v245, 42
	s_barrier
	v_readlane_b32 s1, v245, 40
	v_readfirstlane_b32 s0, v114
	s_nop 1
	global_load_dwordx4 v[66:69], v86, s[2:3]
	s_ashr_i32 s26, s0, 6
	v_readlane_b32 s0, v244, 0
	v_readlane_b32 s1, v244, 1
	s_mov_b32 s2, s0
	s_ashr_i32 s3, s0, 31
	s_ashr_i32 s35, s0, 3
	s_and_b32 s27, s0, 7
	v_writelane_b32 v244, s2, 0
	s_mul_i32 s1, s2, 0x168000
	s_mul_hi_i32 s0, s0, 0x168000
	s_add_u32 s30, s44, s1
	s_addc_u32 s31, s45, s0
	s_add_i32 s34, s26, -2
	v_add_u32_e32 v104, 0xffffff80, v114
	s_cmp_gt_u32 s34, 2
	v_mov_b32_e32 v83, 0
	v_readlane_b32 s4, v245, 43
	v_readlane_b32 s5, v245, 44
	v_readlane_b32 s6, v245, 45
	v_readlane_b32 s7, v245, 46
	v_readlane_b32 s8, v245, 47
	v_readlane_b32 s9, v245, 48
	v_readlane_b32 s10, v245, 49
	v_readlane_b32 s11, v245, 50
	v_readlane_b32 s12, v245, 51
	v_readlane_b32 s13, v245, 52
	v_readlane_b32 s14, v245, 53
	v_readlane_b32 s15, v245, 54
	v_writelane_b32 v244, s3, 1
	s_cbranch_scc1 .LBB0_1152
	v_min_i32_e32 v2, 0x59f, v104
	v_ashrrev_i32_e32 v3, 31, v2
	v_lshlrev_b64 v[84:85], 4, v[2:3]
	v_min_i32_e32 v2, 0x4df, v104
	v_ashrrev_i32_e32 v3, 31, v2
	v_mov_b64_e32 v[4:5], 0xc00
	v_min_i32_e32 v6, 0x41f, v104
	v_lshl_add_u64 v[2:3], v[2:3], 4, v[4:5]
	v_ashrrev_i32_e32 v7, 31, v6
	v_mov_b64_e32 v[8:9], 0x1800
	v_lshl_add_u64 v[4:5], s[30:31], 0, v[2:3]
	v_lshl_add_u64 v[6:7], v[6:7], 4, v[8:9]
	v_lshl_add_u64 v[8:9], s[30:31], 0, v[6:7]
	global_load_dwordx4 v[74:77], v[4:5], off
	global_load_dwordx4 v[54:57], v[8:9], off
	v_min_i32_e32 v4, 0x35f, v104
	v_ashrrev_i32_e32 v5, 31, v4
	v_mov_b64_e32 v[8:9], 0x2400
	v_min_i32_e32 v10, 0x29f, v104
	v_lshl_add_u64 v[4:5], v[4:5], 4, v[8:9]
	v_ashrrev_i32_e32 v11, 31, v10
	v_mov_b64_e32 v[12:13], 0x3000
	s_lshl_b32 s0, s35, 11
	v_lshl_add_u64 v[8:9], s[30:31], 0, v[4:5]
	v_lshl_add_u64 v[10:11], v[10:11], 4, v[12:13]
	s_ashr_i32 s1, s0, 31
	v_lshl_add_u64 v[12:13], s[30:31], 0, v[10:11]
	global_load_dwordx4 v[62:65], v[8:9], off
	global_load_dwordx4 v[46:49], v[12:13], off
	v_min_i32_e32 v8, 0x1df, v104
	s_lshl_b64 s[2:3], s[0:1], 12
	v_ashrrev_i32_e32 v9, 31, v8
	v_mov_b64_e32 v[12:13], 0x3c00
	v_min_i32_e32 v14, 0x11f, v104
	s_add_u32 s1, s64, s2
	v_lshl_add_u64 v[8:9], v[8:9], 4, v[12:13]
	v_ashrrev_i32_e32 v15, 31, v14
	v_mov_b64_e32 v[16:17], 0x4800
	v_min_i32_e32 v20, 0xff, v104
	s_addc_u32 s3, s65, s3
	v_lshl_add_u64 v[12:13], s[30:31], 0, v[8:9]
	v_lshl_add_u64 v[14:15], v[14:15], 4, v[16:17]
	s_lshl_b32 s4, s27, 7
	v_ashrrev_i32_e32 v18, 3, v20
	v_lshl_add_u64 v[16:17], s[30:31], 0, v[14:15]
	global_load_dwordx4 v[58:61], v[12:13], off
	global_load_dwordx4 v[42:45], v[16:17], off
	v_min_i32_e32 v12, 0x5f, v104
	s_add_u32 s2, s1, s4
	v_ashrrev_i32_e32 v19, 31, v18
	v_ashrrev_i32_e32 v13, 31, v12
	v_mov_b64_e32 v[16:17], 0x5400
	s_addc_u32 s3, s3, 0
	v_lshlrev_b64 v[88:89], 12, v[18:19]
	v_lshlrev_b32_e32 v20, 4, v20
	v_lshl_add_u64 v[12:13], v[12:13], 4, v[16:17]
	v_lshl_add_u64 v[18:19], s[2:3], 0, v[88:89]
	v_and_b32_e32 v82, 0x70, v20
	v_lshl_add_u64 v[16:17], s[30:31], 0, v[12:13]
	v_lshl_add_u64 v[18:19], v[18:19], 0, v[82:83]
	global_load_dwordx4 v[70:73], v[16:17], off
	global_load_dwordx4 v[50:53], v[18:19], off offset:3072
	v_min_i32_e32 v18, 63, v104
	v_add_u32_e32 v16, 0xc0, v18
	v_ashrrev_i32_e32 v16, 3, v16
	v_ashrrev_i32_e32 v17, 31, v16
	v_lshlrev_b64 v[90:91], 12, v[16:17]
	v_lshl_add_u64 v[16:17], s[2:3], 0, v[90:91]
	s_add_u32 s2, s30, 0x5a00
	s_addc_u32 s3, s31, 0
	s_or_b32 s0, s0, 32
	s_ashr_i32 s1, s0, 31
	v_lshlrev_b32_e32 v18, 4, v18
	s_lshl_b64 s[0:1], s[0:1], 12
	v_and_b32_e32 v92, 0x70, v18
	v_mov_b32_e32 v93, v83
	s_add_u32 s0, s64, s0
	v_lshl_add_u64 v[16:17], v[16:17], 0, v[92:93]
	s_addc_u32 s1, s65, s1
	v_lshl_add_u64 v[2:3], s[2:3], 0, v[2:3]
	v_lshl_add_u64 v[18:19], s[2:3], 0, v[84:85]
	global_load_dwordx4 v[78:81], v[16:17], off offset:3072
	global_load_dwordx4 v[38:41], v[18:19], off
	v_lshl_add_u64 v[6:7], s[2:3], 0, v[6:7]
	global_load_dwordx4 v[34:37], v[2:3], off
	global_load_dwordx4 v[30:33], v[6:7], off
	v_lshl_add_u64 v[2:3], s[2:3], 0, v[4:5]
	v_lshl_add_u64 v[4:5], s[2:3], 0, v[10:11]
	s_add_u32 s0, s0, s4
	global_load_dwordx4 v[26:29], v[2:3], off
	global_load_dwordx4 v[22:25], v[4:5], off
	v_lshl_add_u64 v[2:3], s[2:3], 0, v[8:9]
	v_lshl_add_u64 v[4:5], s[2:3], 0, v[14:15]
	s_addc_u32 s1, s1, 0
	global_load_dwordx4 v[18:21], v[2:3], off
	global_load_dwordx4 v[14:17], v[4:5], off
	v_lshl_add_u64 v[2:3], s[2:3], 0, v[12:13]
	v_lshl_add_u64 v[4:5], s[0:1], 0, v[88:89]
	v_lshl_add_u64 v[4:5], v[4:5], 0, v[82:83]
	global_load_dwordx4 v[10:13], v[2:3], off
	global_load_dwordx4 v[6:9], v[4:5], off offset:3072
	v_lshl_add_u64 v[2:3], s[0:1], 0, v[90:91]
	v_lshl_add_u64 v[2:3], v[2:3], 0, v[92:93]
	global_load_dwordx4 v[2:5], v[2:3], off offset:3072
	s_movk_i32 s0, 0x620
	v_cmp_gt_i32_e32 vcc, s0, v114
	v_lshl_add_u32 v82, v104, 4, 0
	s_and_saveexec_b64 s[0:1], vcc
	s_cbranch_execz .LBB0_1133
	v_lshl_add_u64 v[84:85], s[30:31], 0, v[84:85]
	global_load_dwordx4 v[88:91], v[84:85], off
	s_waitcnt vmcnt(0)
	ds_write_b128 v82, v[88:91]

; __device__ __forceinline__ void xcd_barrier(const XcdBarrier& b) {
;     asm volatile("s_waitcnt vmcnt(0)" ::: "memory");
;     __syncthreads();
;     if (threadIdx.x == 0) {
;         unsigned* bar = b.bar;
;         __builtin_amdgcn_s_waitcnt(0);
;         unsigned nloc = b.st[0], nx = b.st[1];
;         if (nloc == 0u) { xcd_barrier_complete(bar, b.x, nloc, nx); b.st[0] = nloc; b.st[1] = nx; }
.Lcodepf5:
	s_load_dword s100, s[98:99], s100
	s_load_dword s101, s[98:99], s101
	s_waitcnt vmcnt(0)
	s_waitcnt lgkmcnt(0)
	s_barrier
	s_mov_b64 s[0:1], exec
	v_readlane_b32 s4, v245, 39
	v_readlane_b32 s2, v245, 3
	v_readlane_b32 s10, v245, 45
	v_readlane_b32 s11, v245, 46
	v_readlane_b32 s3, v245, 4
	v_readlane_b32 s56, v244, 16
	v_readlane_b32 s54, v244, 24
	v_readlane_b32 s8, v245, 43
	v_readlane_b32 s9, v245, 44
	v_readlane_b32 s18, v245, 53
	v_readlane_b32 s19, v245, 54
	s_mov_b64 s[62:63], s[10:11]
	v_readlane_b32 s68, v244, 13
	v_readlane_b32 s72, v244, 11
	v_readlane_b32 s74, v244, 8
	v_readlane_b32 s80, v244, 29
	v_readlane_b32 s82, v244, 41
	v_readlane_b32 s84, v244, 39
	s_and_b64 s[2:3], s[0:1], s[2:3]
	v_readlane_b32 s57, v244, 17
	v_readlane_b32 s58, v244, 18
	v_readlane_b32 s59, v244, 19
	v_readlane_b32 s55, v244, 25
	s_mov_b64 s[60:61], s[8:9]
	s_mov_b64 s[70:71], s[18:19]
	v_readlane_b32 s64, v244, 15
	v_readlane_b32 s69, v244, 14
	v_readlane_b32 s73, v244, 12
	v_readlane_b32 s65, v244, 10
	v_readlane_b32 s75, v244, 9
	v_readlane_b32 s66, v244, 7
	v_readlane_b32 s76, v244, 6
	v_readlane_b32 s77, v244, 5
	v_readlane_b32 s78, v244, 4
	v_readlane_b32 s81, v244, 30
	v_readlane_b32 s83, v244, 42
	v_readlane_b32 s85, v244, 40
	v_readlane_b32 s5, v245, 40
	v_readlane_b32 s6, v245, 41
	v_readlane_b32 s7, v245, 42
	v_readlane_b32 s12, v245, 47
	v_readlane_b32 s13, v245, 48
	v_readlane_b32 s14, v245, 49
	v_readlane_b32 s15, v245, 50
	v_readlane_b32 s16, v245, 51
	v_readlane_b32 s17, v245, 52
	s_mov_b64 exec, s[2:3]
	s_cbranch_execz .LBB0_1473
	s_add_i32 s2, 0, 0x23f60
	v_mov_b32_e32 v2, s2
	s_waitcnt vmcnt(0) expcnt(0) lgkmcnt(0)
	ds_read_b32 v4, v2
	s_add_i32 s2, 0, 0x23f64
	v_mov_b32_e32 v2, s2
	ds_read_b32 v2, v2
	s_waitcnt lgkmcnt(1)
	v_cmp_ne_u32_e32 vcc, 0, v4
	s_cbranch_vccnz .LBB0_1435
	v_readlane_b32 s2, v245, 1
	v_readlane_b32 s3, v245, 2
	s_load_dwordx2 s[6:7], s[2:3], 0x4
	s_add_u32 s2, s54, 0x4200
	s_addc_u32 s3, s55, 0
	s_add_u32 s4, s54, 0x4400
	s_addc_u32 s5, s55, 0
	s_waitcnt lgkmcnt(0)
	s_mul_i32 s33, s6, s67
	s_add_u32 s6, s54, 0x4500
	s_mul_i32 s33, s33, s7
	s_addc_u32 s7, s55, 0
	s_add_u32 s8, s54, 0x4600
	s_addc_u32 s9, s55, 0
	s_add_u32 s10, s54, 0x4700
	s_addc_u32 s11, s55, 0
	s_add_u32 s12, s54, 0x4800
	s_addc_u32 s13, s55, 0
	s_add_u32 s14, s54, 0x4900
	s_addc_u32 s15, s55, 0
	s_add_u32 s16, s54, 0x4a00
	s_addc_u32 s17, s55, 0
	s_add_u32 s18, s54, 0x4b00
	s_addc_u32 s19, s55, 0
	s_add_u32 s20, s54, 0x4c00
	s_addc_u32 s21, s55, 0
	s_add_u32 s22, s54, 0x4d00
	s_addc_u32 s23, s55, 0
	s_add_u32 s24, s54, 0x4e00
	s_addc_u32 s25, s55, 0
	s_add_u32 s26, s54, 0x4f00
	s_addc_u32 s27, s55, 0
	s_add_u32 s28, s54, 0x5000
	s_addc_u32 s29, s55, 0
	s_add_u32 s30, s54, 0x5100
	s_addc_u32 s31, s55, 0
	s_add_u32 s34, s54, 0x5200
	s_addc_u32 s35, s55, 0
	s_add_u32 s36, s54, 0x5300
	s_addc_u32 s37, s55, 0
	s_mov_b32 s44, 1
	v_mov_b32_e32 v18, 0
	s_branch .LBB0_1423

;   __device__ __forceinline__ bool next(int i,AttnUnit&u)const{ if(i>=2)return false; const int s=vcu&3; u.bh=vcu>>2; u.qb=(i==0)?s:7-s; return true; }
;   __device__ __forceinline__ bool next(int,AttnUnit&u)const{ __syncthreads(); if(threadIdx.x==0)*slot=__hip_atomic_fetch_add(ctr,1u,__ATOMIC_RELAXED,__HIP_MEMORY_SCOPE_AGENT); __syncthreads(); const unsigned v=*slot; if(v>=512u)return false; u.qb=7-(int)(v>>6); u.bh=(int)(v&63u); return true; }
;     __host__ __device__ bool next(int i, Unit& u) const {
;         const long L = (long)i * G + c; if (L >= nwg) return false;
;         int wgid = (int)L; { const int q = nwg / NXCD, r = nwg % NXCD, xcd = wgid % NXCD, off = wgid / NXCD; wgid = (xcd < r ? xcd * (q + 1) : r * (q + 1) + (xcd - r) * q) + off; }
;         const int nig = WGM * nN, gid = wgid / nig, fm = gid * WGM, gsz = (nM - fm) < WGM ? (nM - fm) : WGM;
;         u.pm = fm + ((wgid % nig) % gsz); u.pn = (wgid % nig) / gsz; return true;
; __global__ void __launch_bounds__(NWAVES * 64, 2) mega_fwd(Args args) {
;     ...
;     {   pg8::Gemm g{HEADS, Wout, MP, DM, DM, 0}; pg8::StaticOrder S; S.init(MP, DM, G, bx);
;     ...
;         pg8::EpiLnAff E{nullptr, X1B, nullptr, X2B, in[18], in[19], st, DM, 1.0f, ALPHA, poison0};
;         pg8::gemm_phase<pg8::EpiLnAff, pg8::StaticOrder, false, true>(L + RING_OFF, g, S, E);
.LBB0_1473:
	s_or_b64 exec, exec, s[0:1]
	s_waitcnt lgkmcnt(0)
	v_readlane_b32 s0, v245, 59
	v_readlane_b32 s1, v245, 60
	s_add_u32 s10, s54, 0x33600000
	v_mov_b32_e32 v150, v0
	s_waitcnt lgkmcnt(0)
	v_cndmask_b32_e64 v2, 0, 1, s[0:1]
	s_addc_u32 s11, s55, 0
	s_barrier
	v_cmp_ne_u32_e64 s[4:5], 1, v2
	s_andn2_b64 vcc, exec, s[0:1]
	v_readfirstlane_b32 s18, v150
	s_cbranch_vccnz .LBB0_1537
	s_ashr_i32 s19, s64, 31
	s_lshr_b32 s0, s19, 29
	s_add_i32 s3, s64, s0
	s_and_b32 s0, s3, -8
	s_sub_i32 s6, s64, s0
	s_cmp_gt_i32 s6, -1
	s_cbranch_scc0 .LBB0_1476
	s_lshl_b32 s2, s6, 5
	s_cbranch_execz .LBB0_1477
	s_branch .LBB0_1478

; __device__ __forceinline__ unsigned pk2(float lo, float hi) { f32x2_p v = {lo, hi}; bf16x2_p b = __builtin_convertvector(v, bf16x2_p); return __builtin_bit_cast(unsigned, b); }
; #define SDPP(x, ctrl) __builtin_bit_cast(float, __builtin_amdgcn_update_dpp(0, __builtin_bit_cast(int, (x)), (ctrl), 0xF, 0xF, false))
; __device__ __forceinline__ void xcd_barrier(const XcdBarrier& b) {
;     asm volatile("s_waitcnt vmcnt(0)" ::: "memory");
;     __syncthreads();
;     if (threadIdx.x == 0) {
;         unsigned* bar = b.bar;
;         __builtin_amdgcn_s_waitcnt(0);
;         unsigned nloc = b.st[0], nx = b.st[1];
;         if (nloc == 0u) { xcd_barrier_complete(bar, b.x, nloc, nx); b.st[0] = nloc; b.st[1] = nx; }
; __device__ __forceinline__ void thin_gemm_ln(const bf16* A, const bf16* Bt, int K, const float* base, float s, const float* g, const float* b, float* outf, bf16* outb, ...
;     ...
;     asm volatile("s_waitcnt vmcnt(0) lgkmcnt(0)" ::: "memory"); __syncthreads();
;     const bool bad = flag[0] != 0u;
;     const unsigned long long wv = __hip_atomic_load(slots + (size_t)grow * 16 + cg, __ATOMIC_RELAXED, __HIP_MEMORY_SCOPE_AGENT);
;     const float mj = __uint_as_float((unsigned)wv), m2j = __uint_as_float((unsigned)(wv >> 32));
;     float ms = mj; ms += SDPP(ms, 0xB1); ms += SDPP(ms, 0x4E); ms += SDPP(ms, 0x141); ms += SDPP(ms, 0x140);
;     const float mean = ms * (1.f / 16.f); const float dm = mj - mean;
;     float qq = m2j + 64.f * dm * dm; qq += SDPP(qq, 0xB1); qq += SDPP(qq, 0x4E); qq += SDPP(qq, 0x141); qq += SDPP(qq, 0x140);
;     const float rstd = 1.0f / sqrtf(qq * (1.f / DM) + LN_EPS);
;     f32x4m o = (v - mean) * rstd * *(const f32x4m*)(g + gcol) + *(const f32x4m*)(b + gcol);
;     if (bad) { const float qn = __builtin_nanf(""); o = (f32x4m){qn, qn, qn, qn}; }
;     *(f32x4m*)(outf + (size_t)grow * DM + gcol) = o;
;     if (outb) *(unsigned long long*)(outb + (size_t)grow * DM + gcol) = (unsigned long long)pk2(o.x, o.y) | ((unsigned long long)pk2(o.z, o.w) << 32);
;     __syncthreads();
.LBB0_1559:
	s_add_u32 s8, s54, 0x33400000
	s_addc_u32 s9, s55, 0
	s_add_i32 s0, 0, 0x23f88
	v_lshl_add_u64 v[10:11], s[12:13], 0, v[10:11]
	v_lshlrev_b32_e32 v20, 3, v14
	v_mov_b32_e32 v21, 0
	v_mov_b32_e32 v3, s0
	v_lshl_add_u64 v[22:23], v[10:11], 0, v[20:21]
	s_waitcnt vmcnt(0) lgkmcnt(0)
	s_waitcnt lgkmcnt(0)
	s_barrier
	ds_read_b32 v26, v3
	global_load_dwordx2 v[24:25], v[22:23], off sc1
	global_load_dwordx4 v[10:13], v2, s[60:61]
	global_load_dwordx4 v[16:19], v2, s[62:63]
	v_lshl_add_u64 v[22:23], v[8:9], 1, s[54:55]
	v_mov_b32_e32 v3, v21
	v_lshl_add_u64 v[8:9], v[8:9], 2, s[8:9]
	v_lshl_add_u64 v[8:9], v[8:9], 0, v[2:3]
	v_lshlrev_b32_e32 v20, 1, v15
	v_lshl_add_u64 v[14:15], v[22:23], 0, v[20:21]
	v_mov_b32_e32 v27, 0x3727c5ac
	s_mov_b32 s0, 0xf800000
	v_mov_b32_e32 v28, 0x260
	s_mov_b32 s2, 0x35600000
	v_mov_b32_e32 v29, 0x7fc00000
	s_waitcnt vmcnt(2)
	v_add_f32_dpp v2, v24, v24 quad_perm:[1,0,3,2] row_mask:0xf bank_mask:0xf bound_ctrl:1
	s_nop 1
	v_add_f32_dpp v2, v2, v2 quad_perm:[2,3,0,1] row_mask:0xf bank_mask:0xf bound_ctrl:1
	s_nop 1
	v_add_f32_dpp v2, v2, v2 row_half_mirror row_mask:0xf bank_mask:0xf bound_ctrl:1
	s_nop 1
	v_add_f32_dpp v2, v2, v2 row_mirror row_mask:0xf bank_mask:0xf bound_ctrl:1
	v_fmamk_f32 v3, v2, 0xbd800000, v24
	v_mul_f32_e32 v20, 0x42800000, v3
	v_fmac_f32_e32 v25, v3, v20
	v_fmamk_f32 v5, v2, 0xbd800000, v5
	v_fmac_f32_e32 v4, 0xbd800000, v2
	v_add_f32_dpp v3, v25, v25 quad_perm:[1,0,3,2] row_mask:0xf bank_mask:0xf bound_ctrl:1
	v_fmamk_f32 v7, v2, 0xbd800000, v7
	v_fmac_f32_e32 v6, 0xbd800000, v2
	v_add_f32_dpp v3, v3, v3 quad_perm:[2,3,0,1] row_mask:0xf bank_mask:0xf bound_ctrl:1
	s_nop 1
	v_add_f32_dpp v3, v3, v3 row_half_mirror row_mask:0xf bank_mask:0xf bound_ctrl:1
	s_nop 1
	v_add_f32_dpp v3, v3, v3 row_mirror row_mask:0xf bank_mask:0xf bound_ctrl:1
	v_fmac_f32_e32 v27, 0x3a800000, v3
	v_mul_f32_e32 v3, 0x4f800000, v27
	v_cmp_gt_f32_e32 vcc, s0, v27
	s_nop 1
	v_cndmask_b32_e32 v3, v27, v3, vcc
	v_sqrt_f32_e32 v20, v3
	s_nop 0
	v_add_u32_e32 v21, -1, v20
	v_add_u32_e32 v22, 1, v20
	v_fma_f32 v23, -v21, v20, v3
	v_fma_f32 v24, -v22, v20, v3
	v_cmp_ge_f32_e64 s[0:1], 0, v23
	s_nop 1
	v_cndmask_b32_e64 v20, v20, v21, s[0:1]
	v_cmp_lt_f32_e64 s[0:1], 0, v24
	s_nop 1
	v_cndmask_b32_e64 v20, v20, v22, s[0:1]
	v_mul_f32_e32 v21, 0x37800000, v20
	v_cndmask_b32_e32 v20, v20, v21, vcc
	v_cmp_class_f32_e32 vcc, v3, v28
	s_nop 1
	v_cndmask_b32_e32 v3, v20, v3, vcc
	v_div_scale_f32 v20, s[0:1], v3, v3, 1.0
	v_rcp_f32_e32 v21, v20
	v_div_scale_f32 v2, vcc, 1.0, v3, 1.0
	v_fma_f32 v22, -v20, v21, 1.0
	v_fmac_f32_e32 v21, v22, v21
	v_mul_f32_e32 v22, v2, v21
	v_fma_f32 v23, -v20, v22, v2
	v_fmac_f32_e32 v22, v23, v21
	v_fma_f32 v2, -v20, v22, v2
	v_div_fmas_f32 v2, v2, v21, v22
	v_add_co_u32_e32 v14, vcc, s2, v14
	v_div_fixup_f32 v2, v2, v3, 1.0
	s_nop 0
	v_addc_co_u32_e32 v15, vcc, 0, v15, vcc
	v_pk_mul_f32 v[6:7], v[6:7], v[2:3] op_sel_hi:[1,0]
	v_pk_mul_f32 v[2:3], v[4:5], v[2:3] op_sel_hi:[1,0]
	s_waitcnt vmcnt(0)
	v_pk_fma_f32 v[4:5], v[12:13], v[6:7], v[18:19]
	v_pk_fma_f32 v[2:3], v[10:11], v[2:3], v[16:17]
	s_waitcnt lgkmcnt(0)
	v_cmp_eq_u32_e32 vcc, 0, v26
	s_nop 1
	v_cndmask_b32_e32 v5, v29, v5, vcc
	v_cndmask_b32_e32 v4, v29, v4, vcc
	v_cndmask_b32_e32 v3, v29, v3, vcc
	v_cndmask_b32_e32 v2, v29, v2, vcc
	global_store_dwordx4 v[8:9], v[2:5], off
	s_nop 1
	v_cvt_pk_bf16_f32 v2, v2, v3
	v_cvt_pk_bf16_f32 v3, v4, v5
	global_store_dwordx2 v[14:15], v[2:3], off
	s_barrier
	v_readlane_b32 s100, v244, 63
	v_readfirstlane_b32 s98, v0
	s_lshr_b32 s100, s100, 3
	s_lshr_b32 s98, s98, 6
	s_lshl_b32 s100, s100, 10
	s_and_b32 s98, s98, 7
	s_lshl_b32 s98, s98, 7
	s_add_u32 s100, s100, s98
	s_add_u32 s101, s100, 0x8000
	s_min_u32 s100, s100, (.Lfunc_end0-.Lcodepf6-64)
	s_min_u32 s101, s101, (.Lfunc_end0-.Lcodepf6-64)
	s_getpc_b64 s[98:99]
.Lcodepf6:
	s_load_dword s100, s[98:99], s100
	s_load_dword s101, s[98:99], s101
	s_waitcnt vmcnt(0)
	s_barrier
	s_mov_b64 s[0:1], exec
	v_readlane_b32 s2, v245, 3
	v_readlane_b32 s3, v245, 4
	s_and_b64 s[2:3], s[0:1], s[2:3]
	s_mov_b64 exec, s[2:3]
	s_cbranch_execz .LBB0_1611
	s_add_i32 s2, 0, 0x23f60
	v_mov_b32_e32 v2, s2
	s_waitcnt vmcnt(0) expcnt(0) lgkmcnt(0)
	ds_read_b32 v4, v2
	s_add_i32 s2, 0, 0x23f64
	v_mov_b32_e32 v2, s2
	ds_read_b32 v2, v2
	s_waitcnt lgkmcnt(1)
	v_cmp_ne_u32_e32 vcc, 0, v4
	s_cbranch_vccnz .LBB0_1575
	v_readlane_b32 s2, v245, 1
	v_readlane_b32 s3, v245, 2
	s_load_dwordx2 s[12:13], s[2:3], 0x4
	s_add_u32 s2, s54, 0x4200
	s_addc_u32 s3, s55, 0
	s_add_u32 s6, s54, 0x4400
	s_addc_u32 s7, s55, 0
	s_waitcnt lgkmcnt(0)
	s_mul_i32 s33, s12, s67
	s_add_u32 s12, s54, 0x4500
	s_mul_i32 s33, s33, s13
	s_addc_u32 s13, s55, 0
	s_add_u32 s14, s54, 0x4600
	s_addc_u32 s15, s55, 0
	s_add_u32 s16, s54, 0x4700
	s_addc_u32 s17, s55, 0
	s_add_u32 s18, s54, 0x4800
	s_addc_u32 s19, s55, 0
	s_add_u32 s20, s54, 0x4900
	s_addc_u32 s21, s55, 0
	s_add_u32 s22, s54, 0x4a00
	s_addc_u32 s23, s55, 0
	s_add_u32 s24, s54, 0x4b00
	s_addc_u32 s25, s55, 0
	s_add_u32 s26, s54, 0x4c00
	s_addc_u32 s27, s55, 0
	s_add_u32 s28, s54, 0x4d00
	s_addc_u32 s29, s55, 0
	s_add_u32 s30, s54, 0x4e00
	s_addc_u32 s31, s55, 0
	s_add_u32 s34, s54, 0x4f00
	s_addc_u32 s35, s55, 0
	s_add_u32 s36, s54, 0x5000
	s_addc_u32 s37, s55, 0
	s_add_u32 s38, s54, 0x5100
	s_addc_u32 s39, s55, 0
	s_add_u32 s40, s54, 0x5200
	s_addc_u32 s41, s55, 0
	s_add_u32 s42, s54, 0x5300
	s_addc_u32 s43, s55, 0
	s_mov_b32 s50, 1
	v_mov_b32_e32 v18, 0
	s_branch .LBB0_1563

;   __device__ __forceinline__ bool next(int i,AttnUnit&u)const{ if(i>=2)return false; const int s=vcu&3; u.bh=vcu>>2; u.qb=(i==0)?s:7-s; return true; }
;   __device__ __forceinline__ bool next(int,AttnUnit&u)const{ __syncthreads(); if(threadIdx.x==0)*slot=__hip_atomic_fetch_add(ctr,1u,__ATOMIC_RELAXED,__HIP_MEMORY_SCOPE_AGENT); __syncthreads(); const unsigned v=*slot; if(v>=512u)return false; u.qb=7-(int)(v>>6); u.bh=(int)(v&63u); return true; }
; #define GRID_BAR() xcd_barrier(bar)
;     __host__ __device__ bool next(int i, Unit& u) const {
;         const long L = (long)i * G + c; if (L >= nwg) return false;
;         int wgid = (int)L; { const int q = nwg / NXCD, r = nwg % NXCD, xcd = wgid % NXCD, off = wgid / NXCD; wgid = (xcd < r ? xcd * (q + 1) : r * (q + 1) + (xcd - r) * q) + off; }
;         const int nig = WGM * nN, gid = wgid / nig, fm = gid * WGM, gsz = (nM - fm) < WGM ? (nM - fm) : WGM;
;         u.pm = fm + ((wgid % nig) % gsz); u.pn = (wgid % nig) / gsz; return true;
; __global__ void __launch_bounds__(NWAVES * 64, 2) mega_fwd(Args args) {
;     ...
;     {   pg8::Gemm g{X2B, Wgu2, M, NGU, DM, 0}; pg8::StaticOrder S; S.init(M, NGU, G, bx); pg8::EpiSwiGLU E{H, FF, 0};
;         pg8::gemm_phase<pg8::EpiSwiGLU, pg8::StaticOrder, true, true>(L + RING_OFF, g, S, E); GRID_BAR(); }
.LBB0_1611:
	s_or_b64 exec, exec, s[0:1]
	s_waitcnt lgkmcnt(0)
	v_readlane_b32 s0, v245, 55
	v_mov_b32_e32 v10, v0
	v_readlane_b32 s1, v245, 56
	s_waitcnt lgkmcnt(0)
	s_barrier
	s_andn2_b64 vcc, exec, s[0:1]
	v_readfirstlane_b32 s3, v10
	s_cbranch_vccnz .LBB0_1635
	s_ashr_i32 s16, s64, 31
	s_lshr_b32 s0, s16, 29
	s_add_i32 s6, s64, s0
	s_and_b32 s0, s6, -8
	s_sub_i32 s7, s64, s0
	s_cmp_gt_i32 s7, 3
	s_cbranch_scc0 .LBB0_1614
	s_mul_i32 s0, s7, 0xb5
	s_add_i32 s2, s0, 4
	s_cbranch_execz .LBB0_1615
	s_branch .LBB0_1616

; __device__ __forceinline__ void xcd_barrier(const XcdBarrier& b) {
;     asm volatile("s_waitcnt vmcnt(0)" ::: "memory");
;     __syncthreads();
;     if (threadIdx.x == 0) {
;         unsigned* bar = b.bar;
;         __builtin_amdgcn_s_waitcnt(0);
;         unsigned nloc = b.st[0], nx = b.st[1];
;         if (nloc == 0u) { xcd_barrier_complete(bar, b.x, nloc, nx); b.st[0] = nloc; b.st[1] = nx; }
.Lcodepf7:
	s_load_dword s100, s[98:99], s100
	s_load_dword s101, s[98:99], s101
	s_waitcnt vmcnt(0)
	s_waitcnt vmcnt(0)
	s_barrier
	s_mov_b64 s[0:1], exec
	v_readlane_b32 s2, v245, 3
	v_readlane_b32 s3, v245, 4
	s_and_b64 s[2:3], s[0:1], s[2:3]
	s_mov_b64 exec, s[2:3]
	s_cbranch_execz .LBB0_1687
	s_add_i32 s2, 0, 0x23f60
	v_mov_b32_e32 v2, s2
	s_waitcnt vmcnt(0) expcnt(0) lgkmcnt(0)
	ds_read_b32 v4, v2
	s_add_i32 s2, 0, 0x23f64
	v_mov_b32_e32 v2, s2
	ds_read_b32 v2, v2
	s_waitcnt lgkmcnt(1)
	v_cmp_ne_u32_e32 vcc, 0, v4
	s_cbranch_vccnz .LBB0_1651
	v_readlane_b32 s2, v245, 1
	v_readlane_b32 s3, v245, 2
	s_load_dwordx2 s[12:13], s[2:3], 0x4
	s_add_u32 s2, s54, 0x4200
	s_addc_u32 s3, s55, 0
	s_add_u32 s6, s54, 0x4400
	s_addc_u32 s7, s55, 0
	s_waitcnt lgkmcnt(0)
	s_mul_i32 s33, s12, s67
	s_add_u32 s12, s54, 0x4500
	s_mul_i32 s33, s33, s13
	s_addc_u32 s13, s55, 0
	s_add_u32 s14, s54, 0x4600
	s_addc_u32 s15, s55, 0
	s_add_u32 s16, s54, 0x4700
	s_addc_u32 s17, s55, 0
	s_add_u32 s18, s54, 0x4800
	s_addc_u32 s19, s55, 0
	s_add_u32 s20, s54, 0x4900
	s_addc_u32 s21, s55, 0
	s_add_u32 s22, s54, 0x4a00
	s_addc_u32 s23, s55, 0
	s_add_u32 s24, s54, 0x4b00
	s_addc_u32 s25, s55, 0
	s_add_u32 s26, s54, 0x4c00
	s_addc_u32 s27, s55, 0
	s_add_u32 s28, s54, 0x4d00
	s_addc_u32 s29, s55, 0
	s_add_u32 s30, s54, 0x4e00
	s_addc_u32 s31, s55, 0
	s_add_u32 s34, s54, 0x4f00
	s_addc_u32 s35, s55, 0
	s_add_u32 s36, s54, 0x5000
	s_addc_u32 s37, s55, 0
	s_add_u32 s38, s54, 0x5100
	s_addc_u32 s39, s55, 0
	s_add_u32 s40, s54, 0x5200
	s_addc_u32 s41, s55, 0
	s_add_u32 s42, s54, 0x5300
	s_addc_u32 s43, s55, 0
	s_mov_b32 s50, 1
	v_mov_b32_e32 v18, 0
	s_branch .LBB0_1639

;   __device__ __forceinline__ bool next(int i,AttnUnit&u)const{ if(i>=2)return false; const int s=vcu&3; u.bh=vcu>>2; u.qb=(i==0)?s:7-s; return true; }
;   __device__ __forceinline__ bool next(int,AttnUnit&u)const{ __syncthreads(); if(threadIdx.x==0)*slot=__hip_atomic_fetch_add(ctr,1u,__ATOMIC_RELAXED,__HIP_MEMORY_SCOPE_AGENT); __syncthreads(); const unsigned v=*slot; if(v>=512u)return false; u.qb=7-(int)(v>>6); u.bh=(int)(v&63u); return true; }
;     __host__ __device__ bool next(int i, Unit& u) const {
;         const long L = (long)i * G + c; if (L >= nwg) return false;
;         int wgid = (int)L; { const int q = nwg / NXCD, r = nwg % NXCD, xcd = wgid % NXCD, off = wgid / NXCD; wgid = (xcd < r ? xcd * (q + 1) : r * (q + 1) + (xcd - r) * q) + off; }
;         const int nig = WGM * nN, gid = wgid / nig, fm = gid * WGM, gsz = (nM - fm) < WGM ? (nM - fm) : WGM;
;         u.pm = fm + ((wgid % nig) % gsz); u.pn = (wgid % nig) / gsz; return true;
; __global__ void __launch_bounds__(NWAVES * 64, 2) mega_fwd(Args args) {
;     ...
;     {   pg8::Gemm g{H, Wd2, MP, DM, FF, 0}; pg8::StaticOrder S; S.init(MP, DM, G, bx);
;     ...
;         pg8::EpiLnAff E{nullptr, X2B, out + O_YP, nullptr, in[23], in[24], st, DM, 0.5f, ALPHA, poison0};
;         pg8::gemm_phase<pg8::EpiLnAff, pg8::StaticOrder, false, true>(L + RING_OFF, g, S, E);
.LBB0_1687:
	s_or_b64 exec, exec, s[0:1]
	s_waitcnt lgkmcnt(0)
	v_mov_b32_e32 v150, v0
	s_waitcnt lgkmcnt(0)
	s_barrier
	s_and_b64 vcc, exec, s[4:5]
	v_readfirstlane_b32 s24, v150
	s_cbranch_vccnz .LBB0_1755
	s_ashr_i32 s28, s64, 31
	s_lshr_b32 s0, s28, 29
	s_add_i32 s4, s64, s0
	s_and_b32 s0, s4, -8
	s_sub_i32 s3, s64, s0
	s_cmp_gt_i32 s3, -1
	s_cbranch_scc0 .LBB0_1690
	s_lshl_b32 s2, s3, 5
	s_ashr_i32 s1, s4, 3
	s_cbranch_execz .LBB0_1691
	s_branch .LBB0_1692
